# phase 6 banded tiles: 17 of the 20 epilogue loads (x1b, pl, ss2) issued inside K stage 14 after the last DMA pieces; taken with v_mov at first use
# baseline (speedup 1.0000x reference)
.LBB0_1039:
	s_lshl_b32 s8, s11, 7
	s_ashr_i32 s9, s8, 31
	s_lshl_b64 s[12:13], s[8:9], 11
	v_lshl_add_u64 v[98:99], v[114:115], 0, s[12:13]
	v_add_co_u32_e32 v4, vcc, s21, v98
	s_lshl_b32 s10, s10, 7
	s_nop 0
	v_addc_co_u32_e32 v5, vcc, 0, v99, vcc
	v_add_co_u32_e32 v6, vcc, s22, v98
	s_ashr_i32 s11, s10, 31
	s_nop 0
	v_addc_co_u32_e32 v7, vcc, 0, v99, vcc
	s_lshl_b64 s[14:15], s[10:11], 11
	v_add_u32_e32 v234, s8, v130
	v_lshlrev_b32_e32 v235, 2, v234
	v_lshlrev_b32_e32 v234, 11, v234
	v_or_b32_e32 v236, s10, v134
	v_lshl_add_u32 v234, v236, 1, v234
	v_add_u32_e32 v236, 0x8000, v234
	v_add_u32_e32 v168, 0x10000, v234
	v_add_u32_e32 v169, 0x18000, v234
	s_barrier
	s_add_u32 m0, s98, 0x1000
	v_lshl_add_u64 v[46:47], v[4:5], 0, v[238:239]
	global_load_lds_dwordx4 v[46:47], off
	s_add_u32 m0, s98, 0x2000
	v_lshl_add_u64 v[62:63], v[6:7], 0, v[238:239]
	global_load_lds_dwordx4 v[62:63], off
	v_add_co_u32_e32 v4, vcc, s23, v98
	s_waitcnt lgkmcnt(0)
	v_lshl_add_u64 v[2:3], v[116:117], 0, s[14:15]
	v_addc_co_u32_e32 v5, vcc, 0, v99, vcc
	v_add_co_u32_e32 v6, vcc, s21, v2
	s_mov_b32 m0, s98
	v_lshl_add_u64 v[50:51], v[98:99], 0, v[238:239]
	global_load_lds_dwordx4 v[50:51], off
	s_add_u32 m0, s98, 0x4000
	v_lshl_add_u64 v[82:83], v[2:3], 0, v[238:239]
	global_load_lds_dwordx4 v[82:83], off
	v_addc_co_u32_e32 v7, vcc, 0, v3, vcc
	s_add_u32 m0, s98, 0x3000
	v_lshl_add_u64 v[66:67], v[4:5], 0, v[238:239]
	global_load_lds_dwordx4 v[66:67], off
	s_add_u32 m0, s98, 0x5000
	v_lshl_add_u64 v[86:87], v[6:7], 0, v[238:239]
	global_load_lds_dwordx4 v[86:87], off
	v_add_co_u32_e32 v4, vcc, s22, v2
	v_mov_b32_e32 v78, 0
	v_addc_co_u32_e32 v5, vcc, 0, v3, vcc
	v_add_co_u32_e32 v2, vcc, s23, v2
	s_mov_b32 s11, 0
	s_nop 0
	v_addc_co_u32_e32 v3, vcc, 0, v3, vcc
	s_add_u32 m0, s98, 0x6000
	v_lshl_add_u64 v[90:91], v[4:5], 0, v[238:239]
	global_load_lds_dwordx4 v[90:91], off
	s_add_u32 m0, s98, 0x7000
	v_lshl_add_u64 v[94:95], v[2:3], 0, v[238:239]
	global_load_lds_dwordx4 v[94:95], off
	s_mov_b64 s[12:13], 0
	s_mov_b32 s9, 0
	v_mov_b32_e32 v79, v78
	v_mov_b32_e32 v80, v78
	v_mov_b32_e32 v81, v78
	v_mov_b32_e32 v74, v78
	v_mov_b32_e32 v75, v78
	v_mov_b32_e32 v76, v78
	v_mov_b32_e32 v77, v78
	v_mov_b32_e32 v70, v78
	v_mov_b32_e32 v71, v78
	v_mov_b32_e32 v72, v78
	v_mov_b32_e32 v73, v78
	v_mov_b32_e32 v58, v78
	v_mov_b32_e32 v59, v78
	v_mov_b32_e32 v60, v78
	v_mov_b32_e32 v61, v78
	v_mov_b32_e32 v54, v78
	v_mov_b32_e32 v55, v78
	v_mov_b32_e32 v56, v78
	v_mov_b32_e32 v57, v78
	v_mov_b32_e32 v42, v78
	v_mov_b32_e32 v43, v78
	v_mov_b32_e32 v44, v78
	v_mov_b32_e32 v45, v78
	v_mov_b32_e32 v38, v78
	v_mov_b32_e32 v39, v78
	v_mov_b32_e32 v40, v78
	v_mov_b32_e32 v41, v78
	v_lshl_add_u64 v[100:101], v[118:119], 0, s[14:15]
	v_mov_b32_e32 v34, v78
	v_mov_b32_e32 v35, v78
	v_mov_b32_e32 v36, v78
	v_mov_b32_e32 v37, v78
	v_mov_b32_e32 v30, v78
	v_mov_b32_e32 v31, v78
	v_mov_b32_e32 v32, v78
	v_mov_b32_e32 v33, v78
	v_mov_b32_e32 v26, v78
	v_mov_b32_e32 v27, v78
	v_mov_b32_e32 v28, v78
	v_mov_b32_e32 v29, v78
	v_mov_b32_e32 v22, v78
	v_mov_b32_e32 v23, v78
	v_mov_b32_e32 v24, v78
	v_mov_b32_e32 v25, v78
	v_mov_b32_e32 v18, v78
	v_mov_b32_e32 v19, v78
	v_mov_b32_e32 v20, v78
	v_mov_b32_e32 v21, v78
	v_mov_b32_e32 v14, v78
	v_mov_b32_e32 v15, v78
	v_mov_b32_e32 v16, v78
	v_mov_b32_e32 v17, v78
	v_mov_b32_e32 v10, v78
	v_mov_b32_e32 v11, v78
	v_mov_b32_e32 v12, v78
	v_mov_b32_e32 v13, v78
	v_mov_b32_e32 v6, v78
	v_mov_b32_e32 v7, v78
	v_mov_b32_e32 v8, v78
	v_mov_b32_e32 v9, v78
	v_mov_b32_e32 v2, v78
	v_mov_b32_e32 v3, v78
	v_mov_b32_e32 v4, v78
	v_mov_b32_e32 v5, v78
	s_waitcnt lgkmcnt(0)
	s_add_u32 m0, s98, 0x8000
	v_lshl_add_u64 v[50:51], v[50:51], 0, v[242:243]
	global_load_lds_dwordx4 v[50:51], off
	s_add_u32 m0, s98, 0x9000
	v_lshl_add_u64 v[46:47], v[46:47], 0, v[242:243]
	global_load_lds_dwordx4 v[46:47], off
	s_add_u32 m0, s98, 0xa000
	v_lshl_add_u64 v[62:63], v[62:63], 0, v[242:243]
	global_load_lds_dwordx4 v[62:63], off
	s_add_u32 m0, s98, 0xb000
	v_lshl_add_u64 v[66:67], v[66:67], 0, v[242:243]
	global_load_lds_dwordx4 v[66:67], off
	s_mov_b32 s100, 0
	s_mov_b32 s101, 0x4000
	s_waitcnt vmcnt(4)
	s_barrier
	s_branch .LBB0_1041

.Ldqs_12:
	s_cmp_gt_u32 s9, 14
	s_cbranch_scc1 .Ldqv_12
	s_waitcnt vmcnt(4)
	s_branch .Ldqx_12
.Ldqv_12:
	s_waitcnt vmcnt(17)
.Ldqx_12:
	s_cmpk_lg_i32 s12, 0x800
	s_mov_b32 s11, s14
	s_waitcnt lgkmcnt(0)
	s_barrier
	s_cbranch_scc0 .LBB0_1047

.Ldq_12_4:
	s_cmp_lg_u32 s9, 14
	s_cbranch_scc1 .Ldqy_n
	global_load_dword v230, v235, s[0:1]
	global_load_dwordx4 v[174:177], v234, s[54:55]
	global_load_dwordx4 v[178:181], v234, s[6:7]
	global_load_dwordx4 v[182:185], v234, s[54:55] offset:64
	global_load_dwordx4 v[186:189], v234, s[6:7] offset:64
	global_load_dwordx4 v[190:193], v236, s[54:55]
	global_load_dwordx4 v[194:197], v236, s[6:7]
	global_load_dwordx4 v[198:201], v236, s[54:55] offset:64
	global_load_dword v231, v235, s[0:1] offset:64
	global_load_dwordx4 v[202:205], v236, s[6:7] offset:64
	global_load_dwordx4 v[206:209], v168, s[54:55]
	global_load_dwordx4 v[210:213], v168, s[54:55] offset:64
	global_load_dwordx4 v[214:217], v168, s[6:7]
	global_load_dwordx4 v[218:221], v168, s[6:7] offset:64
	global_load_dword v232, v235, s[0:1] offset:128
	global_load_dwordx4 v[222:225], v169, s[54:55]
	global_load_dwordx4 v[226:229], v169, s[6:7]

.LBB0_1047:
	v_add_u32_e32 v46, s8, v130
	v_ashrrev_i32_e32 v47, 31, v46
	v_lshl_add_u64 v[64:65], v[46:47], 2, s[0:1]
	v_or_b32_e32 v48, s10, v134
	v_lshlrev_b64 v[50:51], 11, v[46:47]
	v_ashrrev_i32_e32 v49, 31, v48
	v_lshl_add_u64 v[52:53], s[54:55], 0, v[50:51]
	v_lshl_add_u64 v[62:63], s[6:7], 0, v[50:51]
	v_lshlrev_b64 v[120:121], 1, v[48:49]
	v_lshl_add_u64 v[48:49], v[52:53], 0, v[120:121]
	v_lshl_add_u64 v[52:53], v[62:63], 0, v[120:121]
	v_or_b32_e32 v62, 16, v46
	v_or_b32_e32 v64, 32, v46
	v_or_b32_e32 v46, 48, v46
	v_ashrrev_i32_e32 v63, 31, v62
	v_ashrrev_i32_e32 v65, 31, v64
	v_ashrrev_i32_e32 v47, 31, v46
	v_lshlrev_b64 v[126:127], 11, v[62:63]
	v_lshlrev_b64 v[124:125], 11, v[64:65]
	v_lshlrev_b64 v[122:123], 11, v[46:47]
	v_lshl_add_u64 v[156:157], v[46:47], 2, s[0:1]
	v_lshl_add_u64 v[46:47], s[60:61], 0, v[50:51]
	v_lshl_add_u64 v[50:51], s[54:55], 0, v[126:127]
	v_lshl_add_u64 v[66:67], s[6:7], 0, v[126:127]
	v_lshl_add_u64 v[68:69], s[54:55], 0, v[124:125]
	v_lshl_add_u64 v[82:83], s[6:7], 0, v[124:125]
	v_lshl_add_u64 v[62:63], v[62:63], 2, s[0:1]
	v_lshl_add_u64 v[64:65], v[64:65], 2, s[0:1]
	v_lshl_add_u64 v[84:85], s[54:55], 0, v[122:123]
	v_lshl_add_u64 v[86:87], s[6:7], 0, v[122:123]
	v_lshl_add_u64 v[158:159], v[46:47], 0, v[120:121]
	v_lshl_add_u64 v[46:47], v[50:51], 0, v[120:121]
	v_lshl_add_u64 v[48:49], v[66:67], 0, v[120:121]
	v_lshl_add_u64 v[50:51], v[68:69], 0, v[120:121]
	v_lshl_add_u64 v[52:53], v[82:83], 0, v[120:121]
	v_lshl_add_u64 v[160:161], v[84:85], 0, v[120:121]
	v_lshl_add_u64 v[162:163], v[86:87], 0, v[120:121]
	s_nop 0
	global_load_dwordx4 v[46:49], v[160:161], off offset:64
	global_load_dword v139, v[156:157], off
	global_load_dwordx4 v[50:53], v[162:163], off offset:64
	s_waitcnt vmcnt(3)
	v_mov_b32_e32 v164, v230
	v_mov_b32_e32 v140, v174
	v_mov_b32_e32 v141, v175
	v_mov_b32_e32 v142, v176
	v_mov_b32_e32 v143, v177
	v_mov_b32_e32 v144, v178
	v_mov_b32_e32 v145, v179
	v_mov_b32_e32 v146, v180
	v_mov_b32_e32 v147, v181
	v_mov_b32_e32 v148, v182
	v_mov_b32_e32 v149, v183
	v_mov_b32_e32 v150, v184
	v_mov_b32_e32 v151, v185
	v_mov_b32_e32 v152, v186
	v_mov_b32_e32 v153, v187
	v_mov_b32_e32 v154, v188
	v_mov_b32_e32 v155, v189
	v_mov_b32_e32 v106, v190
	v_mov_b32_e32 v107, v191
	v_mov_b32_e32 v108, v192
	v_mov_b32_e32 v109, v193
	v_mov_b32_e32 v110, v194
	v_mov_b32_e32 v111, v195
	v_mov_b32_e32 v112, v196
	v_mov_b32_e32 v113, v197
	v_mov_b32_e32 v98, v198
	v_mov_b32_e32 v99, v199
	v_mov_b32_e32 v100, v200
	v_mov_b32_e32 v101, v201
	v_mov_b32_e32 v165, v231
	v_mov_b32_e32 v102, v202
	v_mov_b32_e32 v103, v203
	v_mov_b32_e32 v104, v204
	v_mov_b32_e32 v105, v205
	v_mov_b32_e32 v90, v206
	v_mov_b32_e32 v91, v207
	v_mov_b32_e32 v92, v208
	v_mov_b32_e32 v93, v209
	v_mov_b32_e32 v82, v210
	v_mov_b32_e32 v83, v211
	v_mov_b32_e32 v84, v212
	v_mov_b32_e32 v85, v213
	v_mov_b32_e32 v94, v214
	v_mov_b32_e32 v95, v215
	v_mov_b32_e32 v96, v216
	v_mov_b32_e32 v97, v217
	v_mov_b32_e32 v86, v218
	v_mov_b32_e32 v87, v219
	v_mov_b32_e32 v88, v220
	v_mov_b32_e32 v89, v221
	v_mov_b32_e32 v166, v232
	v_mov_b32_e32 v62, v222
	v_mov_b32_e32 v63, v223
	v_mov_b32_e32 v64, v224
	v_mov_b32_e32 v65, v225
	v_mov_b32_e32 v66, v226
	v_mov_b32_e32 v67, v227
	v_mov_b32_e32 v68, v228
	v_mov_b32_e32 v69, v229
	v_fmamk_f32 v156, v164, 0x3a800000, v138
	v_mul_f32_e32 v157, 0x4b800000, v156
	v_cmp_gt_f32_e32 vcc, s24, v156
	s_waitcnt vmcnt(17)
	v_lshlrev_b32_e32 v160, 16, v144
	v_cndmask_b32_e32 v162, v156, v157, vcc
	v_rsq_f32_e32 v163, v162
	v_lshlrev_b32_e32 v156, 16, v140
	v_and_b32_e32 v157, 0xffff0000, v140
	v_and_b32_e32 v161, 0xffff0000, v144
	v_mul_f32_e32 v164, 0x45800000, v163
	v_cndmask_b32_e32 v164, v163, v164, vcc
	v_mul_f32_e32 v78, v78, v164
	v_mul_f32_e32 v79, v79, v164
	v_mul_f32_e32 v80, v80, v164
	v_mul_f32_e32 v81, v81, v164
	v_mul_f32_e32 v74, v74, v164
	v_mul_f32_e32 v75, v75, v164
	v_mul_f32_e32 v78, 0xbfb8aa3b, v78
	v_mul_f32_e32 v79, 0xbfb8aa3b, v79
	v_mul_f32_e32 v80, 0xbfb8aa3b, v80
	v_mul_f32_e32 v81, 0xbfb8aa3b, v81
	v_mul_f32_e32 v163, 0xbfb8aa3b, v74
	v_mul_f32_e32 v167, 0xbfb8aa3b, v75
	v_exp_f32_e32 v74, v78
	v_exp_f32_e32 v75, v79
	v_exp_f32_e32 v78, v80
	v_exp_f32_e32 v79, v81
	v_exp_f32_e32 v163, v163
	v_exp_f32_e32 v167, v167
	v_add_f32_e32 v78, 1.0, v78
	v_add_f32_e32 v79, 1.0, v79
	v_rcp_f32_e32 v78, v78
	v_rcp_f32_e32 v79, v79
	v_mul_f32_e32 v76, v76, v164
	v_lshlrev_b32_e32 v140, 16, v141
	v_lshlrev_b32_e32 v144, 16, v145
	v_and_b32_e32 v141, 0xffff0000, v141
	v_and_b32_e32 v145, 0xffff0000, v145
	v_mul_f32_e32 v76, 0xbfb8aa3b, v76
	v_lshlrev_b32_e32 v162, 16, v142
	v_pk_fma_f32 v[78:79], v[78:79], v[144:145], v[140:141]
	v_add_f32_e32 v140, 1.0, v163
	v_and_b32_e32 v163, 0xffff0000, v142
	v_exp_f32_e32 v142, v76
	v_mul_f32_e32 v76, v77, v164
	v_mul_f32_e32 v76, 0xbfb8aa3b, v76
	v_add_f32_e32 v141, 1.0, v167
	v_exp_f32_e32 v77, v76
	v_rcp_f32_e32 v140, v140
	v_rcp_f32_e32 v141, v141
	v_add_f32_e32 v74, 1.0, v74
	v_add_f32_e32 v75, 1.0, v75
	v_lshlrev_b32_e32 v144, 16, v146
	v_and_b32_e32 v145, 0xffff0000, v146
	v_add_f32_e32 v142, 1.0, v142
	v_add_f32_e32 v77, 1.0, v77
	v_rcp_f32_e32 v74, v74
	v_rcp_f32_e32 v75, v75
	v_pk_fma_f32 v[140:141], v[140:141], v[144:145], v[162:163]
	v_rcp_f32_e32 v144, v142
	v_rcp_f32_e32 v145, v77
	v_lshlrev_b32_e32 v76, 16, v143
	v_lshlrev_b32_e32 v142, 16, v147
	v_and_b32_e32 v77, 0xffff0000, v143
	v_and_b32_e32 v143, 0xffff0000, v147
	v_pk_fma_f32 v[80:81], v[74:75], v[160:161], v[156:157]
	v_pk_fma_f32 v[142:143], v[144:145], v[142:143], v[76:77]
	v_mul_f32_e32 v70, v70, v164
	v_cvt_pk_bf16_f32 v74, v80, v81
	v_cvt_pk_bf16_f32 v75, v78, v79
	v_cvt_pk_bf16_f32 v76, v140, v141
	v_cvt_pk_bf16_f32 v77, v142, v143
	v_mul_f32_e32 v70, 0xbfb8aa3b, v70
	global_store_dwordx4 v[158:159], v[74:77], off
	v_mul_f32_e32 v58, v58, v164
	v_mul_f32_e32 v58, 0xbfb8aa3b, v58
	v_pk_mul_f32 v[74:75], v[140:141], v[140:141]
	v_exp_f32_e32 v140, v70
	v_mul_f32_e32 v70, v71, v164
	v_mul_f32_e32 v70, 0xbfb8aa3b, v70
	v_exp_f32_e32 v71, v70
	v_add_f32_e32 v140, 1.0, v140
	v_rcp_f32_e32 v140, v140
	v_pk_mul_f32 v[76:77], v[142:143], v[142:143]
	v_add_f32_e32 v71, 1.0, v71
	v_rcp_f32_e32 v141, v71
	s_waitcnt vmcnt(17)
	v_lshlrev_b32_e32 v70, 16, v148
	s_waitcnt vmcnt(16)
	v_lshlrev_b32_e32 v142, 16, v152
	v_and_b32_e32 v71, 0xffff0000, v148
	v_and_b32_e32 v143, 0xffff0000, v152
	v_pk_fma_f32 v[140:141], v[140:141], v[142:143], v[70:71]
	v_mul_f32_e32 v70, v72, v164
	v_mul_f32_e32 v70, 0xbfb8aa3b, v70
	v_exp_f32_e32 v71, v70
	v_mul_f32_e32 v70, v73, v164
	v_mul_f32_e32 v70, 0xbfb8aa3b, v70
	v_exp_f32_e32 v73, v70
	v_add_f32_e32 v71, 1.0, v71
	v_rcp_f32_e32 v72, v71
	v_lshlrev_b32_e32 v70, 16, v149
	v_add_f32_e32 v71, 1.0, v73
	v_rcp_f32_e32 v73, v71
	v_lshlrev_b32_e32 v142, 16, v153
	v_and_b32_e32 v71, 0xffff0000, v149
	v_and_b32_e32 v143, 0xffff0000, v153
	v_pk_fma_f32 v[72:73], v[72:73], v[142:143], v[70:71]
	v_mul_f32_e32 v60, v60, v164
	v_cvt_pk_bf16_f32 v71, v72, v73
	v_pk_mul_f32 v[142:143], v[72:73], v[72:73]
	v_exp_f32_e32 v72, v58
	v_mul_f32_e32 v58, v59, v164
	v_mul_f32_e32 v58, 0xbfb8aa3b, v58
	v_exp_f32_e32 v59, v58
	v_add_f32_e32 v72, 1.0, v72
	v_rcp_f32_e32 v72, v72
	v_lshlrev_b32_e32 v58, 16, v150
	v_add_f32_e32 v59, 1.0, v59
	v_rcp_f32_e32 v73, v59
	v_lshlrev_b32_e32 v144, 16, v154
	v_and_b32_e32 v59, 0xffff0000, v150
	v_and_b32_e32 v145, 0xffff0000, v154
	v_mul_f32_e32 v60, 0xbfb8aa3b, v60
	v_pk_fma_f32 v[58:59], v[72:73], v[144:145], v[58:59]
	v_exp_f32_e32 v72, v60
	v_mul_f32_e32 v60, v61, v164
	v_mul_f32_e32 v60, 0xbfb8aa3b, v60
	v_exp_f32_e32 v61, v60
	v_add_f32_e32 v72, 1.0, v72
	v_rcp_f32_e32 v72, v72
	v_lshlrev_b32_e32 v60, 16, v151
	v_add_f32_e32 v61, 1.0, v61
	v_rcp_f32_e32 v73, v61
	v_lshlrev_b32_e32 v144, 16, v155
	v_and_b32_e32 v61, 0xffff0000, v151
	v_and_b32_e32 v145, 0xffff0000, v155
	v_pk_fma_f32 v[60:61], v[72:73], v[144:145], v[60:61]
	v_pk_mul_f32 v[80:81], v[80:81], v[80:81]
	v_cvt_pk_bf16_f32 v70, v140, v141
	v_cvt_pk_bf16_f32 v72, v58, v59
	v_cvt_pk_bf16_f32 v73, v60, v61
	v_pk_mul_f32 v[78:79], v[78:79], v[78:79]
	global_store_dwordx4 v[158:159], v[70:73], off offset:64
	v_pk_mul_f32 v[140:141], v[140:141], v[140:141]
	v_pk_mul_f32 v[58:59], v[58:59], v[58:59]
	v_add_f32_e32 v70, v74, v75
	v_add_f32_e32 v71, v80, v81
	v_add_f32_e32 v70, v76, v70
	v_add_f32_e32 v71, v78, v71
	v_add_f32_e32 v70, v77, v70
	v_add_f32_e32 v71, v79, v71
	v_add_f32_e32 v70, v71, v70
	v_add_f32_e32 v71, v140, v141
	v_add_f32_e32 v71, v142, v71
	v_add_f32_e32 v71, v143, v71
	v_add_f32_e32 v58, v58, v59
	s_waitcnt vmcnt(13)
	v_fmamk_f32 v59, v165, 0x3a800000, v138
	v_add_f32_e32 v70, v71, v70
	v_mul_f32_e32 v71, 0x4b800000, v59
	v_cmp_gt_f32_e32 vcc, s24, v59
	v_pk_mul_f32 v[60:61], v[60:61], v[60:61]
	v_lshlrev_b32_e32 v72, 16, v110
	v_cndmask_b32_e32 v59, v59, v71, vcc
	v_rsq_f32_e32 v59, v59
	v_add_f32_e32 v58, v60, v58
	v_add_f32_e32 v58, v61, v58
	v_add_f32_e32 v58, v58, v70
	v_mul_f32_e32 v60, 0x45800000, v59
	v_cndmask_b32_e32 v59, v59, v60, vcc
	v_mul_f32_e32 v54, v54, v59
	v_mul_f32_e32 v54, 0xbfb8aa3b, v54
	v_exp_f32_e32 v70, v54
	v_mul_f32_e32 v54, v55, v59
	v_mul_f32_e32 v54, 0xbfb8aa3b, v54
	v_exp_f32_e32 v55, v54
	v_add_f32_e32 v70, 1.0, v70
	v_rcp_f32_e32 v70, v70
	v_mul_f32_e32 v56, v56, v59
	v_add_f32_e32 v55, 1.0, v55
	v_rcp_f32_e32 v71, v55
	v_lshlrev_b32_e32 v54, 16, v106
	v_and_b32_e32 v55, 0xffff0000, v106
	v_and_b32_e32 v73, 0xffff0000, v110
	v_mul_f32_e32 v56, 0xbfb8aa3b, v56
	v_pk_fma_f32 v[54:55], v[70:71], v[72:73], v[54:55]
	v_exp_f32_e32 v70, v56
	v_mul_f32_e32 v56, v57, v59
	v_mul_f32_e32 v56, 0xbfb8aa3b, v56
	v_exp_f32_e32 v57, v56
	v_add_f32_e32 v70, 1.0, v70
	v_rcp_f32_e32 v70, v70
	v_mul_f32_e32 v42, v42, v59
	v_add_f32_e32 v57, 1.0, v57
	v_rcp_f32_e32 v71, v57
	v_lshlrev_b32_e32 v56, 16, v107
	v_lshlrev_b32_e32 v72, 16, v111
	v_and_b32_e32 v57, 0xffff0000, v107
	v_and_b32_e32 v73, 0xffff0000, v111
	v_mul_f32_e32 v42, 0xbfb8aa3b, v42
	v_pk_fma_f32 v[56:57], v[70:71], v[72:73], v[56:57]
	v_exp_f32_e32 v72, v42
	v_mul_f32_e32 v42, v43, v59
	v_mul_f32_e32 v42, 0xbfb8aa3b, v42
	v_exp_f32_e32 v43, v42
	v_add_f32_e32 v72, 1.0, v72
	v_rcp_f32_e32 v72, v72
	v_mul_f32_e32 v44, v44, v59
	v_add_f32_e32 v43, 1.0, v43
	v_rcp_f32_e32 v73, v43
	v_lshlrev_b32_e32 v42, 16, v108
	v_lshlrev_b32_e32 v74, 16, v112
	v_and_b32_e32 v43, 0xffff0000, v108
	v_and_b32_e32 v75, 0xffff0000, v112
	v_mul_f32_e32 v44, 0xbfb8aa3b, v44
	v_pk_fma_f32 v[42:43], v[72:73], v[74:75], v[42:43]
	v_exp_f32_e32 v72, v44
	v_mul_f32_e32 v44, v45, v59
	v_mul_f32_e32 v44, 0xbfb8aa3b, v44
	v_exp_f32_e32 v45, v44
	v_add_f32_e32 v72, 1.0, v72
	v_rcp_f32_e32 v72, v72
	v_lshlrev_b32_e32 v44, 16, v109
	v_add_f32_e32 v45, 1.0, v45
	v_rcp_f32_e32 v73, v45
	v_lshlrev_b32_e32 v74, 16, v113
	v_and_b32_e32 v45, 0xffff0000, v109
	v_and_b32_e32 v75, 0xffff0000, v113
	v_lshl_add_u64 v[60:61], s[60:61], 0, v[126:127]
	v_pk_fma_f32 v[44:45], v[72:73], v[74:75], v[44:45]
	v_mul_f32_e32 v38, v38, v59
	v_cvt_pk_bf16_f32 v70, v54, v55
	v_cvt_pk_bf16_f32 v71, v56, v57
	v_lshl_add_u64 v[60:61], v[60:61], 0, v[120:121]
	v_cvt_pk_bf16_f32 v72, v42, v43
	v_cvt_pk_bf16_f32 v73, v44, v45
	v_mul_f32_e32 v38, 0xbfb8aa3b, v38
	global_store_dwordx4 v[60:61], v[70:73], off
	v_mul_f32_e32 v40, v40, v59
	v_mul_f32_e32 v40, 0xbfb8aa3b, v40
	v_exp_f32_e32 v70, v38
	v_mul_f32_e32 v38, v39, v59
	v_mul_f32_e32 v38, 0xbfb8aa3b, v38
	v_exp_f32_e32 v39, v38
	v_add_f32_e32 v70, 1.0, v70
	v_rcp_f32_e32 v70, v70
	v_lshlrev_b32_e32 v38, 16, v98
	v_add_f32_e32 v39, 1.0, v39
	v_rcp_f32_e32 v71, v39
	s_waitcnt vmcnt(13)
	v_lshlrev_b32_e32 v72, 16, v102
	v_and_b32_e32 v39, 0xffff0000, v98
	v_and_b32_e32 v73, 0xffff0000, v102
	v_pk_fma_f32 v[38:39], v[70:71], v[72:73], v[38:39]
	v_exp_f32_e32 v70, v40
	v_mul_f32_e32 v40, v41, v59
	v_mul_f32_e32 v40, 0xbfb8aa3b, v40
	v_exp_f32_e32 v41, v40
	v_add_f32_e32 v70, 1.0, v70
	v_rcp_f32_e32 v70, v70
	v_mul_f32_e32 v34, v34, v59
	v_add_f32_e32 v41, 1.0, v41
	v_rcp_f32_e32 v71, v41
	v_lshlrev_b32_e32 v40, 16, v99
	v_lshlrev_b32_e32 v72, 16, v103
	v_and_b32_e32 v41, 0xffff0000, v99
	v_and_b32_e32 v73, 0xffff0000, v103
	v_mul_f32_e32 v34, 0xbfb8aa3b, v34
	v_pk_fma_f32 v[40:41], v[70:71], v[72:73], v[40:41]
	v_exp_f32_e32 v72, v34
	v_mul_f32_e32 v34, v35, v59
	v_mul_f32_e32 v34, 0xbfb8aa3b, v34
	v_exp_f32_e32 v35, v34
	v_add_f32_e32 v72, 1.0, v72
	v_rcp_f32_e32 v72, v72
	v_mul_f32_e32 v36, v36, v59
	v_add_f32_e32 v35, 1.0, v35
	v_rcp_f32_e32 v73, v35
	v_lshlrev_b32_e32 v34, 16, v100
	v_lshlrev_b32_e32 v74, 16, v104
	v_and_b32_e32 v35, 0xffff0000, v100
	v_and_b32_e32 v75, 0xffff0000, v104
	v_mul_f32_e32 v36, 0xbfb8aa3b, v36
	v_pk_fma_f32 v[34:35], v[72:73], v[74:75], v[34:35]
	v_exp_f32_e32 v72, v36
	v_mul_f32_e32 v36, v37, v59
	v_mul_f32_e32 v36, 0xbfb8aa3b, v36
	v_exp_f32_e32 v37, v36
	v_add_f32_e32 v59, 1.0, v72
	v_rcp_f32_e32 v72, v59
	v_lshlrev_b32_e32 v36, 16, v101
	v_add_f32_e32 v37, 1.0, v37
	v_rcp_f32_e32 v73, v37
	v_lshlrev_b32_e32 v74, 16, v105
	v_and_b32_e32 v37, 0xffff0000, v101
	v_and_b32_e32 v75, 0xffff0000, v105
	s_waitcnt vmcnt(8)
	v_fmamk_f32 v59, v166, 0x3a800000, v138
	v_pk_fma_f32 v[36:37], v[72:73], v[74:75], v[36:37]
	v_mul_f32_e32 v72, 0x4b800000, v59
	v_cmp_gt_f32_e32 vcc, s24, v59
	v_cvt_pk_bf16_f32 v70, v38, v39
	v_cvt_pk_bf16_f32 v71, v40, v41
	v_cndmask_b32_e32 v59, v59, v72, vcc
	v_rsq_f32_e32 v59, v59
	v_cvt_pk_bf16_f32 v72, v34, v35
	v_cvt_pk_bf16_f32 v73, v36, v37
	global_store_dwordx4 v[60:61], v[70:73], off offset:64
	v_mul_f32_e32 v60, 0x45800000, v59
	v_cndmask_b32_e32 v59, v59, v60, vcc
	v_mul_f32_e32 v30, v30, v59
	v_mul_f32_e32 v30, 0xbfb8aa3b, v30
	v_exp_f32_e32 v70, v30
	v_mul_f32_e32 v30, v31, v59
	v_mul_f32_e32 v30, 0xbfb8aa3b, v30
	v_exp_f32_e32 v31, v30
	v_add_f32_e32 v70, 1.0, v70
	v_rcp_f32_e32 v70, v70
	v_mul_f32_e32 v32, v32, v59
	v_add_f32_e32 v31, 1.0, v31
	v_rcp_f32_e32 v71, v31
	v_lshlrev_b32_e32 v30, 16, v90
	v_lshlrev_b32_e32 v72, 16, v94
	v_and_b32_e32 v31, 0xffff0000, v90
	v_and_b32_e32 v73, 0xffff0000, v94
	v_mul_f32_e32 v32, 0xbfb8aa3b, v32
	v_pk_fma_f32 v[30:31], v[70:71], v[72:73], v[30:31]
	v_exp_f32_e32 v70, v32
	v_mul_f32_e32 v32, v33, v59
	v_mul_f32_e32 v32, 0xbfb8aa3b, v32
	v_exp_f32_e32 v33, v32
	v_add_f32_e32 v70, 1.0, v70
	v_rcp_f32_e32 v70, v70
	v_mul_f32_e32 v26, v26, v59
	v_add_f32_e32 v33, 1.0, v33
	v_rcp_f32_e32 v71, v33
	v_lshlrev_b32_e32 v32, 16, v91
	v_lshlrev_b32_e32 v72, 16, v95
	v_and_b32_e32 v33, 0xffff0000, v91
	v_and_b32_e32 v73, 0xffff0000, v95
	v_mul_f32_e32 v26, 0xbfb8aa3b, v26
	v_pk_fma_f32 v[32:33], v[70:71], v[72:73], v[32:33]
	v_exp_f32_e32 v72, v26
	v_mul_f32_e32 v26, v27, v59
	v_mul_f32_e32 v26, 0xbfb8aa3b, v26
	v_exp_f32_e32 v27, v26
	v_add_f32_e32 v72, 1.0, v72
	v_rcp_f32_e32 v72, v72
	v_mul_f32_e32 v28, v28, v59
	v_add_f32_e32 v27, 1.0, v27
	v_rcp_f32_e32 v73, v27
	v_lshlrev_b32_e32 v26, 16, v92
	v_lshlrev_b32_e32 v74, 16, v96
	v_and_b32_e32 v27, 0xffff0000, v92
	v_and_b32_e32 v75, 0xffff0000, v96
	v_mul_f32_e32 v28, 0xbfb8aa3b, v28
	v_pk_fma_f32 v[26:27], v[72:73], v[74:75], v[26:27]
	v_exp_f32_e32 v72, v28
	v_mul_f32_e32 v28, v29, v59
	v_mul_f32_e32 v28, 0xbfb8aa3b, v28
	v_exp_f32_e32 v29, v28
	v_add_f32_e32 v72, 1.0, v72
	v_rcp_f32_e32 v72, v72
	v_lshlrev_b32_e32 v28, 16, v93
	v_add_f32_e32 v29, 1.0, v29
	v_rcp_f32_e32 v73, v29
	v_lshlrev_b32_e32 v74, 16, v97
	v_and_b32_e32 v29, 0xffff0000, v93
	v_and_b32_e32 v75, 0xffff0000, v97
	v_lshl_add_u64 v[60:61], s[60:61], 0, v[124:125]
	v_pk_fma_f32 v[28:29], v[72:73], v[74:75], v[28:29]
	v_mul_f32_e32 v22, v22, v59
	v_cvt_pk_bf16_f32 v70, v30, v31
	v_cvt_pk_bf16_f32 v71, v32, v33
	v_lshl_add_u64 v[60:61], v[60:61], 0, v[120:121]
	v_cvt_pk_bf16_f32 v72, v26, v27
	v_cvt_pk_bf16_f32 v73, v28, v29
	v_mul_f32_e32 v22, 0xbfb8aa3b, v22
	global_store_dwordx4 v[60:61], v[70:73], off
	v_mul_f32_e32 v24, v24, v59
	v_mul_f32_e32 v24, 0xbfb8aa3b, v24
	v_exp_f32_e32 v70, v22
	v_mul_f32_e32 v22, v23, v59
	v_mul_f32_e32 v22, 0xbfb8aa3b, v22
	v_exp_f32_e32 v23, v22
	v_add_f32_e32 v70, 1.0, v70
	v_rcp_f32_e32 v70, v70
	v_lshlrev_b32_e32 v22, 16, v82
	v_add_f32_e32 v23, 1.0, v23
	v_rcp_f32_e32 v71, v23
	v_lshlrev_b32_e32 v72, 16, v86
	v_and_b32_e32 v23, 0xffff0000, v82
	v_and_b32_e32 v73, 0xffff0000, v86
	v_pk_fma_f32 v[22:23], v[70:71], v[72:73], v[22:23]
	v_exp_f32_e32 v70, v24
	v_mul_f32_e32 v24, v25, v59
	v_mul_f32_e32 v24, 0xbfb8aa3b, v24
	v_exp_f32_e32 v25, v24
	v_add_f32_e32 v70, 1.0, v70
	v_rcp_f32_e32 v70, v70
	v_mul_f32_e32 v18, v18, v59
	v_add_f32_e32 v25, 1.0, v25
	v_rcp_f32_e32 v71, v25
	v_lshlrev_b32_e32 v24, 16, v83
	v_lshlrev_b32_e32 v72, 16, v87
	v_and_b32_e32 v25, 0xffff0000, v83
	v_and_b32_e32 v73, 0xffff0000, v87
	v_mul_f32_e32 v18, 0xbfb8aa3b, v18
	v_pk_fma_f32 v[24:25], v[70:71], v[72:73], v[24:25]
	v_exp_f32_e32 v72, v18
	v_mul_f32_e32 v18, v19, v59
	v_mul_f32_e32 v18, 0xbfb8aa3b, v18
	v_exp_f32_e32 v19, v18
	v_add_f32_e32 v72, 1.0, v72
	v_rcp_f32_e32 v72, v72
	v_mul_f32_e32 v20, v20, v59
	v_add_f32_e32 v19, 1.0, v19
	v_rcp_f32_e32 v73, v19
	v_lshlrev_b32_e32 v18, 16, v84
	v_lshlrev_b32_e32 v74, 16, v88
	v_and_b32_e32 v19, 0xffff0000, v84
	v_and_b32_e32 v75, 0xffff0000, v88
	v_mul_f32_e32 v20, 0xbfb8aa3b, v20
	v_pk_fma_f32 v[18:19], v[72:73], v[74:75], v[18:19]
	v_exp_f32_e32 v72, v20
	v_mul_f32_e32 v20, v21, v59
	v_mul_f32_e32 v20, 0xbfb8aa3b, v20
	v_exp_f32_e32 v21, v20
	v_add_f32_e32 v59, 1.0, v72
	v_rcp_f32_e32 v72, v59
	v_lshlrev_b32_e32 v20, 16, v85
	v_add_f32_e32 v21, 1.0, v21
	v_rcp_f32_e32 v73, v21
	v_lshlrev_b32_e32 v74, 16, v89
	v_and_b32_e32 v21, 0xffff0000, v85
	v_and_b32_e32 v75, 0xffff0000, v89
	s_waitcnt vmcnt(6)
	v_fmamk_f32 v59, v139, 0x3a800000, v138
	v_pk_fma_f32 v[20:21], v[72:73], v[74:75], v[20:21]
	v_mul_f32_e32 v72, 0x4b800000, v59
	v_cmp_gt_f32_e32 vcc, s24, v59
	v_cvt_pk_bf16_f32 v70, v22, v23
	v_cvt_pk_bf16_f32 v71, v24, v25
	v_cndmask_b32_e32 v59, v59, v72, vcc
	v_rsq_f32_e32 v59, v59
	v_cvt_pk_bf16_f32 v72, v18, v19
	v_cvt_pk_bf16_f32 v73, v20, v21
	global_store_dwordx4 v[60:61], v[70:73], off offset:64
	v_mul_f32_e32 v60, 0x45800000, v59
	v_cndmask_b32_e32 v59, v59, v60, vcc
	v_mul_f32_e32 v14, v14, v59
	v_mul_f32_e32 v14, 0xbfb8aa3b, v14
	v_exp_f32_e32 v60, v14
	v_mul_f32_e32 v14, v15, v59
	v_mul_f32_e32 v14, 0xbfb8aa3b, v14
	v_exp_f32_e32 v15, v14
	v_add_f32_e32 v60, 1.0, v60
	v_rcp_f32_e32 v60, v60
	v_mul_f32_e32 v16, v16, v59
	v_add_f32_e32 v15, 1.0, v15
	v_rcp_f32_e32 v61, v15
	v_lshlrev_b32_e32 v14, 16, v62
	v_lshlrev_b32_e32 v72, 16, v66
	v_and_b32_e32 v15, 0xffff0000, v62
	v_and_b32_e32 v73, 0xffff0000, v66
	v_mul_f32_e32 v16, 0xbfb8aa3b, v16
	v_pk_fma_f32 v[14:15], v[60:61], v[72:73], v[14:15]
	v_exp_f32_e32 v60, v16
	v_mul_f32_e32 v16, v17, v59
	v_mul_f32_e32 v16, 0xbfb8aa3b, v16
	v_exp_f32_e32 v17, v16
	v_add_f32_e32 v60, 1.0, v60
	v_rcp_f32_e32 v60, v60
	v_mul_f32_e32 v10, v10, v59
	v_add_f32_e32 v17, 1.0, v17
	v_rcp_f32_e32 v61, v17
	v_lshlrev_b32_e32 v16, 16, v63
	v_lshlrev_b32_e32 v62, 16, v67
	v_and_b32_e32 v17, 0xffff0000, v63
	v_and_b32_e32 v63, 0xffff0000, v67
	v_mul_f32_e32 v10, 0xbfb8aa3b, v10
	v_pk_fma_f32 v[16:17], v[60:61], v[62:63], v[16:17]
	v_exp_f32_e32 v62, v10
	v_mul_f32_e32 v10, v11, v59
	v_mul_f32_e32 v10, 0xbfb8aa3b, v10
	v_exp_f32_e32 v11, v10
	v_add_f32_e32 v62, 1.0, v62
	v_rcp_f32_e32 v62, v62
	v_lshl_add_u64 v[70:71], s[60:61], 0, v[122:123]
	v_add_f32_e32 v11, 1.0, v11
	v_rcp_f32_e32 v63, v11
	v_mul_f32_e32 v12, v12, v59
	v_lshl_add_u64 v[66:67], v[70:71], 0, v[120:121]
	v_lshlrev_b32_e32 v10, 16, v64
	v_lshlrev_b32_e32 v70, 16, v68
	v_and_b32_e32 v11, 0xffff0000, v64
	v_and_b32_e32 v71, 0xffff0000, v68
	v_mul_f32_e32 v12, 0xbfb8aa3b, v12
	v_pk_fma_f32 v[10:11], v[62:63], v[70:71], v[10:11]
	v_exp_f32_e32 v62, v12
	v_mul_f32_e32 v12, v13, v59
	v_mul_f32_e32 v12, 0xbfb8aa3b, v12
	v_exp_f32_e32 v13, v12
	v_add_f32_e32 v62, 1.0, v62
	v_rcp_f32_e32 v62, v62
	v_lshlrev_b32_e32 v12, 16, v65
	v_add_f32_e32 v13, 1.0, v13
	v_rcp_f32_e32 v63, v13
	v_lshlrev_b32_e32 v64, 16, v69
	v_and_b32_e32 v13, 0xffff0000, v65
	v_and_b32_e32 v65, 0xffff0000, v69
	v_pk_fma_f32 v[12:13], v[62:63], v[64:65], v[12:13]
	v_mul_f32_e32 v6, v6, v59
	v_cvt_pk_bf16_f32 v60, v14, v15
	v_cvt_pk_bf16_f32 v61, v16, v17
	v_cvt_pk_bf16_f32 v62, v10, v11
	v_cvt_pk_bf16_f32 v63, v12, v13
	v_mul_f32_e32 v6, 0xbfb8aa3b, v6
	global_store_dwordx4 v[66:67], v[60:63], off
	v_mul_f32_e32 v8, v8, v59
	v_mul_f32_e32 v8, 0xbfb8aa3b, v8
	v_exp_f32_e32 v60, v6
	v_mul_f32_e32 v6, v7, v59
	v_mul_f32_e32 v6, 0xbfb8aa3b, v6
	v_exp_f32_e32 v7, v6
	v_lshlrev_b32_e32 v6, 16, v46
	v_add_f32_e32 v60, 1.0, v60
	v_rcp_f32_e32 v60, v60
	v_add_f32_e32 v7, 1.0, v7
	v_rcp_f32_e32 v61, v7
	v_and_b32_e32 v7, 0xffff0000, v46
	v_exp_f32_e32 v46, v8
	v_mul_f32_e32 v8, v9, v59
	v_mul_f32_e32 v8, 0xbfb8aa3b, v8
	v_exp_f32_e32 v9, v8
	s_waitcnt vmcnt(7)
	v_lshlrev_b32_e32 v62, 16, v50
	v_and_b32_e32 v63, 0xffff0000, v50
	v_add_f32_e32 v46, 1.0, v46
	v_add_f32_e32 v9, 1.0, v9
	v_pk_fma_f32 v[6:7], v[60:61], v[62:63], v[6:7]
	v_rcp_f32_e32 v60, v46
	v_rcp_f32_e32 v61, v9
	v_mul_f32_e32 v2, v2, v59
	v_lshlrev_b32_e32 v8, 16, v47
	v_lshlrev_b32_e32 v46, 16, v51
	v_and_b32_e32 v9, 0xffff0000, v47
	v_and_b32_e32 v47, 0xffff0000, v51
	v_mul_f32_e32 v2, 0xbfb8aa3b, v2
	v_pk_fma_f32 v[8:9], v[60:61], v[46:47], v[8:9]
	v_exp_f32_e32 v46, v2
	v_mul_f32_e32 v2, v3, v59
	v_mul_f32_e32 v2, 0xbfb8aa3b, v2
	v_mul_f32_e32 v4, v4, v59
	v_mul_f32_e32 v5, v5, v59
	v_exp_f32_e32 v3, v2
	v_mul_f32_e32 v4, 0xbfb8aa3b, v4
	v_mul_f32_e32 v5, 0xbfb8aa3b, v5
	v_exp_f32_e32 v4, v4
	v_exp_f32_e32 v5, v5
	v_add_f32_e32 v46, 1.0, v46
	v_add_f32_e32 v3, 1.0, v3
	v_rcp_f32_e32 v46, v46
	v_rcp_f32_e32 v47, v3
	v_add_f32_e32 v4, 1.0, v4
	v_add_f32_e32 v5, 1.0, v5
	ds_bpermute_b32 v59, v135, v58
	v_rcp_f32_e32 v4, v4
	v_rcp_f32_e32 v5, v5
	v_lshlrev_b32_e32 v2, 16, v48
	v_lshlrev_b32_e32 v60, 16, v52
	v_and_b32_e32 v3, 0xffff0000, v48
	v_and_b32_e32 v61, 0xffff0000, v52
	v_pk_fma_f32 v[2:3], v[46:47], v[60:61], v[2:3]
	v_lshlrev_b32_e32 v46, 16, v49
	v_lshlrev_b32_e32 v48, 16, v53
	v_and_b32_e32 v47, 0xffff0000, v49
	v_and_b32_e32 v49, 0xffff0000, v53
	v_pk_fma_f32 v[46:47], v[4:5], v[48:49], v[46:47]
	s_waitcnt lgkmcnt(0)
	v_add_f32_e32 v48, v58, v59
	ds_bpermute_b32 v49, v136, v48
	v_add_u32_e32 v4, s8, v137
	v_cvt_pk_bf16_f32 v50, v6, v7
	v_cvt_pk_bf16_f32 v51, v8, v9
	v_cvt_pk_bf16_f32 v52, v2, v3
	v_cvt_pk_bf16_f32 v53, v46, v47
	v_ashrrev_i32_e32 v5, 31, v4
	global_store_dwordx4 v[66:67], v[50:53], off offset:64
	s_and_saveexec_b64 s[8:9], s[4:5]
	s_cbranch_execz .LBB0_1049
	s_waitcnt lgkmcnt(0)
	v_add_f32_e32 v50, v48, v49
	v_lshl_add_u64 v[48:49], v[4:5], 2, s[2:3]
	global_atomic_add_f32 v[48:49], v50, off
